# v64 mirrored: co-located mixer role split with waves 4-7 pooling in the first pass and waves 0-3 in the second
# baseline (speedup 1.0000x reference)
; #define LAS __attribute__((address_space(3)))
; #define lane (hw_lane())
; __device__ __forceinline__ void sgu_item(LAS unsigned char* wl, const bf16* proj, bf16* ymix, const float* vstat, const float* sgu_g, const bf16* Wm, const float* sgu_b, int chunk, int h, int lane) {
;     ...
;     const int r = lane & 15, q = lane >> 4, c16 = lane & 3, rsub = lane >> 2;
;     LAS f32x2* st = (LAS f32x2*)(wl + 128 * VP2);
; #pragma unroll
;     for (int hh = 0; hh < 2; ++hh) { const f32x4* sp = (const f32x4*)(vstat + (R0 + lane + 64 * hh) * 16);
;         const f32x4 a = sp[0], b = sp[1], c = sp[2], d = sp[3];
;         const float s1 = ((a[0] + a[2]) + (b[0] + b[2])) + ((c[0] + c[2]) + (d[0] + d[2])), s2 = ((a[1] + a[3]) + (b[1] + b[3])) + ((c[1] + c[3]) + (d[1] + d[3]));
;         const float mean = s1 * (1.0f / 512.0f), var = fmaxf(s2 * (1.0f / 512.0f) - mean * mean, 0.f);
;         st[lane + 64 * hh] = (f32x2){mean, __builtin_amdgcn_rsqf(var + EPS)}; }
;     bf16x8 wmf[20];
;     { const bf16* wm = Wm + (size_t)(h * 128 + r) * 128 + q * 8; int f = 0;
; #pragma unroll
;       for (int ks = 0; ks < 4; ++ks)
; #pragma unroll
;         for (int tb = 2 * ks; tb < 8; ++tb) wmf[f++] = *(const bf16x8*)(wm + (size_t)(16 * tb) * 128 + ks * 32); }
;     float bias[8];
; #pragma unroll
;     for (int tb = 0; tb < 8; ++tb) bias[tb] = sgu_b[h * 128 + 16 * tb + r];
; __device__ __forceinline__ void mixer_phase(LAS unsigned char* lds, const bf16* proj, bf16* ymix, const float* vstat, const bf16* WpT, const float* pscale, const float* sgu_g, const bf16* Wm, const float* sgu_b, int pool_first, int pool_step, int pool_limit, int sgu_first, int sgu_step, int sgu_limi ...
;     ...
;     for (int j = sgu_first; j < sgu_limit; j += sgu_step) sgu_item(wl, proj, ymix, vstat, sgu_g, Wm, sgu_b, j >> 2, j & 3, lane);
.LBB0_508:
	v_readlane_b32 s0, v254, 50
	v_readlane_b32 s1, v254, 51
	s_andn2_b64 vcc, exec, s[0:1]
	s_cbranch_vccnz .LBB0_513
	s_cmp_eq_u32 s98, 0
	s_cbranch_scc1 .LBB0_513
	v_readlane_b32 s22, v255, 37
	s_lshl_b32 s86, s22, 9
	v_readlane_b32 s4, v253, 3
	s_lshl_b64 s[0:1], s[86:87], 2
	v_readlane_b32 s14, v253, 13
	v_readlane_b32 s5, v253, 4
	v_readlane_b32 s15, v253, 14
	s_add_u32 s14, s4, s0
	s_waitcnt vmcnt(0)
	v_lshrrev_b32_e32 v0, 1, v81
	v_readlane_b32 s18, v253, 17
	s_addc_u32 s15, s5, s1
	v_and_b32_e32 v2, 24, v0
	v_readlane_b32 s0, v255, 39
	v_readlane_b32 s19, v253, 18
	s_add_u32 s18, s38, 0x25100000
	v_lshlrev_b32_e32 v192, 1, v2
	v_readlane_b32 s1, v255, 40
	s_addc_u32 s19, s39, 0
	v_or_b32_e32 v7, 0x70, v140
	v_lshl_add_u64 v[0:1], s[0:1], 0, v[192:193]
	s_mov_b64 s[0:1], 0x1e40000
	v_lshl_add_u64 v[144:145], v[0:1], 0, s[0:1]
	s_add_u32 s0, s20, 0x10900400
	v_and_b32_e32 v8, 48, v81
	v_and_b32_e32 v143, 15, v81
	v_and_b32_e32 v0, 24, v83
	s_addc_u32 s1, s21, 0
	v_lshl_or_b32 v192, v7, 11, v8
	v_add_u32_e32 v4, s2, v0
	v_bfe_u32 v0, v81, 2, 2
	v_or_b32_e32 v6, 48, v140
	v_lshl_add_u64 v[146:147], s[0:1], 0, v[192:193]
	v_lshl_or_b32 v192, v143, 11, v8
	v_or_b32_e32 v0, v0, v2
	v_lshl_add_u64 v[148:149], s[20:21], 0, v[192:193]
	v_lshl_or_b32 v192, v6, 11, v8
	v_mul_u32_u24_e32 v2, 0x50, v0
	v_lshl_add_u64 v[150:151], s[0:1], 0, v[192:193]
	s_add_u32 s0, s26, 0xf100400
	v_mul_u32_u24_e32 v0, 0xc00, v7
	s_addc_u32 s1, s27, 0
	v_mul_hi_u32_u24_e32 v1, 0xc00, v7
	v_or_b32_e32 v0, v0, v8
	v_lshl_add_u64 v[152:153], s[0:1], 0, v[0:1]
	v_mul_u32_u24_e32 v0, 0xc00, v143
	v_mul_hi_u32_u24_e32 v1, 0xc00, v143
	v_or_b32_e32 v0, v0, v8
	v_lshl_add_u64 v[154:155], s[26:27], 0, v[0:1]
	v_mul_u32_u24_e32 v0, 0xc00, v6
	v_readlane_b32 s23, v255, 38
	v_lshrrev_b32_e32 v3, 2, v140
	v_mul_hi_u32_u24_e32 v1, 0xc00, v6
	v_or_b32_e32 v0, v0, v8
	v_add_u32_e32 v141, s2, v83
	v_lshl_add_u32 v218, v3, 3, s2
	v_lshl_add_u64 v[156:157], s[0:1], 0, v[0:1]
	s_lshl_b64 s[0:1], s[22:23], 11
	v_readlane_b32 s2, v255, 14
	v_mul_u32_u24_e32 v5, 0x50, v3
	v_mul_hi_u32_u24_e32 v1, 0xc00, v3
	v_mul_u32_u24_e32 v0, 0xc00, v3
	v_and_b32_e32 v3, 3, v81
	s_add_u32 s0, s2, s0
	v_readlane_b32 s2, v255, 15
	v_readlane_b32 s7, v253, 6
	v_lshl_or_b32 v0, v3, 4, v0
	v_lshlrev_b32_e32 v192, 5, v3
	s_addc_u32 s1, s2, s1
	v_or_b32_e32 v142, 64, v140
	v_lshl_add_u64 v[158:159], s[26:27], 0, v[0:1]
	v_lshl_add_u64 v[160:161], s[0:1], 0, v[192:193]
	v_add_u32_e32 v219, v4, v5
	v_add_u32_e32 v220, v4, v2
	v_readlane_b32 s4, v254, 62
	v_readlane_b32 s5, v254, 61
	v_readlane_b32 s2, v254, 49
	v_readlane_b32 s7, v254, 63
	v_readlane_b32 s6, v253, 5
	v_readlane_b32 s8, v253, 7
	v_readlane_b32 s9, v253, 8
	v_readlane_b32 s10, v253, 9
	v_readlane_b32 s11, v253, 10
	v_readlane_b32 s12, v253, 11
	v_readlane_b32 s13, v253, 12
	v_readlane_b32 s16, v253, 15
	v_readlane_b32 s17, v253, 16
	s_xor_b32 s5, s5, 4
	s_xor_b32 s4, s4, 0x200
	s_add_i32 s2, s5, 1
